# P6/P10: when a workgroup has no next tile, the last iteration's dummy prefetch re-reads the just-used (L2-hot) k-slices instead of the tile start
# baseline (speedup 1.0000x reference)
.LBB0_944:
	s_ashr_i32 s29, s28, 31
	v_cmp_lt_i64_e32 vcc, s[30:31], v[154:155]
	s_lshl_b64 s[30:31], s[28:29], 20
	s_add_u32 s30, s48, s30
	s_addc_u32 s31, s49, s31
	s_and_b64 s[34:35], vcc, exec
	s_cselect_b32 s29, s31, s39
	s_cselect_b32 s63, s30, s38
	s_cselect_b32 s85, 0, 0xf00
	s_add_u32 s63, s63, s85
	s_addc_u32 s29, s29, 0
	s_ashr_i32 s27, s26, 31
	s_lshl_b64 s[34:35], s[26:27], 20
	s_add_u32 s34, s54, s34
	s_addc_u32 s35, s55, s35
	s_and_b64 s[42:43], vcc, exec
	s_cselect_b32 s27, s35, s41
	s_cselect_b32 s64, s34, s40
	s_cselect_b32 s85, 0, 0xf00
	s_add_u32 s64, s64, s85
	s_addc_u32 s27, s27, 0
	s_add_u32 s38, s38, 0x80080
	s_addc_u32 s39, s39, 0
	s_add_u32 s65, s40, 0x100
	s_addc_u32 s66, s41, 0
	s_mov_b32 s67, -2
	ds_read_b128 v[130:133], v167
	ds_read_b128 v[134:137], v167 offset:1024
	ds_read_b128 v[138:141], v167 offset:2048
	ds_read_b128 v[142:145], v167 offset:3072
	s_add_u32 s40, s38, 0xfff80080
	s_addc_u32 s41, s39, -1
	s_cmp_eq_u32 s67, 28
	s_cselect_b32 s43, s29, s41
	s_cselect_b32 s42, s63, s40
	s_cselect_b32 s41, s27, s66
	s_cselect_b32 s40, s64, s65
	v_lshl_add_u64 v[158:159], s[38:39], 0, v[150:151]
	s_add_i32 m0, s37, 0xc000
	ds_read_b128 v[172:175], v170
	ds_read_b128 v[176:179], v170 offset:1024
	ds_read_b128 v[180:183], v170 offset:2048
	ds_read_b128 v[184:187], v170 offset:3072
	ds_read_b128 v[188:191], v170 offset:4096
	ds_read_b128 v[192:195], v170 offset:5120
	ds_read_b128 v[196:199], v170 offset:6144
	ds_read_b128 v[200:203], v170 offset:7168
	global_load_lds_dwordx4 v[158:159], off
	v_lshl_add_u64 v[158:159], s[38:39], 0, v[152:153]
	s_add_i32 m0, s37, 0xe000
	s_nop 0
	global_load_lds_dwordx4 v[158:159], off
	s_waitcnt lgkmcnt(8)
	s_barrier
	s_waitcnt lgkmcnt(0)
	s_setprio 1
	s_waitcnt lgkmcnt(0)
	v_mfma_f32_16x16x32_bf16 v[126:129], v[130:133], v[172:175], 0
	v_mfma_f32_16x16x32_bf16 v[122:125], v[138:141], v[172:175], 0
	v_mfma_f32_16x16x32_bf16 v[114:117], v[130:133], v[180:183], 0
	v_mfma_f32_16x16x32_bf16 v[106:109], v[138:141], v[180:183], 0
	v_mfma_f32_16x16x32_bf16 v[98:101], v[130:133], v[188:191], 0
	v_mfma_f32_16x16x32_bf16 v[90:93], v[138:141], v[188:191], 0
	v_mfma_f32_16x16x32_bf16 v[82:85], v[130:133], v[196:199], 0
	v_mfma_f32_16x16x32_bf16 v[74:77], v[138:141], v[196:199], 0
	v_mfma_f32_16x16x32_bf16 v[126:129], v[134:137], v[176:179], v[126:129]
	v_mfma_f32_16x16x32_bf16 v[122:125], v[142:145], v[176:179], v[122:125]
	v_mfma_f32_16x16x32_bf16 v[114:117], v[134:137], v[184:187], v[114:117]
	v_mfma_f32_16x16x32_bf16 v[106:109], v[142:145], v[184:187], v[106:109]
	v_mfma_f32_16x16x32_bf16 v[98:101], v[134:137], v[192:195], v[98:101]
	v_mfma_f32_16x16x32_bf16 v[90:93], v[142:145], v[192:195], v[90:93]
	v_mfma_f32_16x16x32_bf16 v[82:85], v[134:137], v[200:203], v[82:85]
	v_mfma_f32_16x16x32_bf16 v[74:77], v[142:145], v[200:203], v[74:77]
	s_setprio 0
	s_barrier
	s_add_i32 s68, s59, s47
	v_lshl_add_u64 v[158:159], s[40:41], 0, v[146:147]
	s_mov_b32 m0, s68
	ds_read_b128 v[204:207], v171
	ds_read_b128 v[208:211], v171 offset:1024
	ds_read_b128 v[212:215], v171 offset:2048
	ds_read_b128 v[216:219], v171 offset:3072
	global_load_lds_dwordx4 v[158:159], off
	v_lshl_add_u64 v[168:169], s[40:41], 0, v[148:149]
	s_add_i32 m0, s68, 0x2000
	s_nop 0
	global_load_lds_dwordx4 v[168:169], off
	s_barrier
	s_waitcnt lgkmcnt(0)
	s_setprio 1
	s_waitcnt lgkmcnt(0)
	v_mfma_f32_16x16x32_bf16 v[118:121], v[204:207], v[172:175], 0
	v_mfma_f32_16x16x32_bf16 v[110:113], v[212:215], v[172:175], 0
	v_mfma_f32_16x16x32_bf16 v[102:105], v[204:207], v[180:183], 0
	v_mfma_f32_16x16x32_bf16 v[94:97], v[212:215], v[180:183], 0
	v_mfma_f32_16x16x32_bf16 v[86:89], v[204:207], v[188:191], 0
	v_mfma_f32_16x16x32_bf16 v[78:81], v[212:215], v[188:191], 0
	v_mfma_f32_16x16x32_bf16 v[70:73], v[204:207], v[196:199], 0
	v_mfma_f32_16x16x32_bf16 v[66:69], v[212:215], v[196:199], 0
	v_mfma_f32_16x16x32_bf16 v[118:121], v[208:211], v[176:179], v[118:121]
	v_mfma_f32_16x16x32_bf16 v[110:113], v[216:219], v[176:179], v[110:113]
	v_mfma_f32_16x16x32_bf16 v[102:105], v[208:211], v[184:187], v[102:105]
	v_mfma_f32_16x16x32_bf16 v[94:97], v[216:219], v[184:187], v[94:97]
	v_mfma_f32_16x16x32_bf16 v[86:89], v[208:211], v[192:195], v[86:89]
	v_mfma_f32_16x16x32_bf16 v[78:81], v[216:219], v[192:195], v[78:81]
	v_mfma_f32_16x16x32_bf16 v[70:73], v[208:211], v[200:203], v[70:73]
	v_mfma_f32_16x16x32_bf16 v[66:69], v[216:219], v[200:203], v[66:69]
	s_setprio 0
	s_mov_b32 m0, s37
	v_lshl_add_u64 v[220:221], s[42:43], 0, v[146:147]
	s_barrier
	ds_read_b128 v[172:175], v170 offset:16384
	ds_read_b128 v[176:179], v170 offset:17408
	ds_read_b128 v[180:183], v170 offset:18432
	ds_read_b128 v[184:187], v170 offset:19456
	ds_read_b128 v[188:191], v170 offset:20480
	ds_read_b128 v[192:195], v170 offset:21504
	ds_read_b128 v[196:199], v170 offset:22528
	ds_read_b128 v[200:203], v170 offset:23552
	global_load_lds_dwordx4 v[220:221], off
	v_lshl_add_u64 v[222:223], s[42:43], 0, v[148:149]
	s_mov_b32 m0, s50
	s_nop 0
	global_load_lds_dwordx4 v[222:223], off
	s_barrier
	s_waitcnt lgkmcnt(0)
	s_setprio 1
	s_waitcnt lgkmcnt(0)
	v_mfma_f32_16x16x32_bf16 v[62:65], v[130:133], v[172:175], 0
	v_mfma_f32_16x16x32_bf16 v[58:61], v[138:141], v[172:175], 0
	v_mfma_f32_16x16x32_bf16 v[54:57], v[130:133], v[180:183], 0
	v_mfma_f32_16x16x32_bf16 v[46:49], v[138:141], v[180:183], 0
	v_mfma_f32_16x16x32_bf16 v[38:41], v[130:133], v[188:191], 0
	v_mfma_f32_16x16x32_bf16 v[30:33], v[138:141], v[188:191], 0
	v_mfma_f32_16x16x32_bf16 v[22:25], v[130:133], v[196:199], 0
	v_mfma_f32_16x16x32_bf16 v[14:17], v[138:141], v[196:199], 0
	v_mfma_f32_16x16x32_bf16 v[62:65], v[134:137], v[176:179], v[62:65]
	v_mfma_f32_16x16x32_bf16 v[58:61], v[142:145], v[176:179], v[58:61]
	v_mfma_f32_16x16x32_bf16 v[54:57], v[134:137], v[184:187], v[54:57]
	v_mfma_f32_16x16x32_bf16 v[46:49], v[142:145], v[184:187], v[46:49]
	v_mfma_f32_16x16x32_bf16 v[38:41], v[134:137], v[192:195], v[38:41]
	v_mfma_f32_16x16x32_bf16 v[30:33], v[142:145], v[192:195], v[30:33]
	v_mfma_f32_16x16x32_bf16 v[22:25], v[134:137], v[200:203], v[22:25]
	v_mfma_f32_16x16x32_bf16 v[14:17], v[142:145], v[200:203], v[14:17]
	s_setprio 0
	s_barrier
	s_add_u32 s68, s40, 0x80000
	s_addc_u32 s69, s41, 0
	s_add_i32 s70, s60, s47
	v_lshl_add_u64 v[130:131], s[68:69], 0, v[146:147]
	s_mov_b32 m0, s70
	s_nop 0
	global_load_lds_dwordx4 v[130:131], off
	v_lshl_add_u64 v[130:131], s[68:69], 0, v[148:149]
	s_add_i32 m0, s70, 0x2000
	s_nop 0
	global_load_lds_dwordx4 v[130:131], off
	s_waitcnt vmcnt(6)
	s_barrier
	s_setprio 1
	v_mfma_f32_16x16x32_bf16 v[50:53], v[204:207], v[172:175], 0
	v_mfma_f32_16x16x32_bf16 v[42:45], v[212:215], v[172:175], 0
	v_mfma_f32_16x16x32_bf16 v[34:37], v[204:207], v[180:183], 0
	v_mfma_f32_16x16x32_bf16 v[26:29], v[212:215], v[180:183], 0
	v_mfma_f32_16x16x32_bf16 v[18:21], v[204:207], v[188:191], 0
	v_mfma_f32_16x16x32_bf16 v[10:13], v[212:215], v[188:191], 0
	v_mfma_f32_16x16x32_bf16 v[6:9], v[204:207], v[196:199], 0
	v_mfma_f32_16x16x32_bf16 v[2:5], v[212:215], v[196:199], 0
	v_mfma_f32_16x16x32_bf16 v[50:53], v[208:211], v[176:179], v[50:53]
	v_mfma_f32_16x16x32_bf16 v[42:45], v[216:219], v[176:179], v[42:45]
	v_mfma_f32_16x16x32_bf16 v[34:37], v[208:211], v[184:187], v[34:37]
	v_mfma_f32_16x16x32_bf16 v[26:29], v[216:219], v[184:187], v[26:29]
	v_mfma_f32_16x16x32_bf16 v[18:21], v[208:211], v[192:195], v[18:21]
	v_mfma_f32_16x16x32_bf16 v[10:13], v[216:219], v[192:195], v[10:13]
	v_mfma_f32_16x16x32_bf16 v[6:9], v[208:211], v[200:203], v[6:9]
	v_mfma_f32_16x16x32_bf16 v[2:5], v[216:219], v[200:203], v[2:5]
	s_setprio 0
	s_add_i32 s68, 0, 0x18000
	v_add_u32_e32 v142, s68, v164
	s_barrier
	ds_read_b128 v[130:133], v142
	ds_read_b128 v[134:137], v142 offset:1024
	ds_read_b128 v[138:141], v142 offset:2048
	ds_read_b128 v[142:145], v142 offset:3072
	s_add_u32 s42, s42, 0x80000
	s_addc_u32 s43, s43, 0
	s_mov_b32 m0, s51
	v_lshl_add_u64 v[204:205], s[42:43], 0, v[146:147]
	ds_read_b128 v[172:175], v170 offset:32768
	ds_read_b128 v[176:179], v170 offset:33792
	ds_read_b128 v[180:183], v170 offset:34816
	ds_read_b128 v[184:187], v170 offset:35840
	ds_read_b128 v[188:191], v170 offset:36864
	ds_read_b128 v[192:195], v170 offset:37888
	ds_read_b128 v[196:199], v170 offset:38912
	ds_read_b128 v[200:203], v170 offset:39936
	global_load_lds_dwordx4 v[204:205], off
	v_lshl_add_u64 v[204:205], s[42:43], 0, v[148:149]
	s_mov_b32 m0, s52
	s_nop 0
	global_load_lds_dwordx4 v[204:205], off
	s_waitcnt lgkmcnt(8)
	s_barrier
	s_waitcnt lgkmcnt(0)
	s_setprio 1
	s_waitcnt lgkmcnt(0)
	v_mfma_f32_16x16x32_bf16 v[126:129], v[130:133], v[172:175], v[126:129]
	v_mfma_f32_16x16x32_bf16 v[122:125], v[138:141], v[172:175], v[122:125]
	v_mfma_f32_16x16x32_bf16 v[114:117], v[130:133], v[180:183], v[114:117]
	v_mfma_f32_16x16x32_bf16 v[106:109], v[138:141], v[180:183], v[106:109]
	v_mfma_f32_16x16x32_bf16 v[98:101], v[130:133], v[188:191], v[98:101]
	v_mfma_f32_16x16x32_bf16 v[90:93], v[138:141], v[188:191], v[90:93]
	v_mfma_f32_16x16x32_bf16 v[82:85], v[130:133], v[196:199], v[82:85]
	v_mfma_f32_16x16x32_bf16 v[74:77], v[138:141], v[196:199], v[74:77]
	v_mfma_f32_16x16x32_bf16 v[126:129], v[134:137], v[176:179], v[126:129]
	v_mfma_f32_16x16x32_bf16 v[122:125], v[142:145], v[176:179], v[122:125]
	v_mfma_f32_16x16x32_bf16 v[114:117], v[134:137], v[184:187], v[114:117]
	v_mfma_f32_16x16x32_bf16 v[106:109], v[142:145], v[184:187], v[106:109]
	v_mfma_f32_16x16x32_bf16 v[98:101], v[134:137], v[192:195], v[98:101]
	v_mfma_f32_16x16x32_bf16 v[90:93], v[142:145], v[192:195], v[90:93]
	v_mfma_f32_16x16x32_bf16 v[82:85], v[134:137], v[200:203], v[82:85]
	v_mfma_f32_16x16x32_bf16 v[74:77], v[142:145], v[200:203], v[74:77]
	s_setprio 0
	s_barrier
	s_add_i32 s42, 0, 0x1c000
	s_add_i32 s43, s68, s47
	v_add_u32_e32 v166, s42, v164
	v_lshl_add_u64 v[158:159], v[158:159], 0, s[14:15]
	s_mov_b32 m0, s43
	ds_read_b128 v[204:207], v166
	ds_read_b128 v[208:211], v166 offset:1024
	ds_read_b128 v[212:215], v166 offset:2048
	ds_read_b128 v[216:219], v166 offset:3072
	global_load_lds_dwordx4 v[158:159], off
	v_lshl_add_u64 v[158:159], v[168:169], 0, s[14:15]
	s_add_i32 m0, s43, 0x2000
	s_nop 0
	global_load_lds_dwordx4 v[158:159], off
	s_barrier
	s_waitcnt lgkmcnt(0)
	s_setprio 1
	s_waitcnt lgkmcnt(0)
	v_mfma_f32_16x16x32_bf16 v[118:121], v[204:207], v[172:175], v[118:121]
	v_mfma_f32_16x16x32_bf16 v[110:113], v[212:215], v[172:175], v[110:113]
	v_mfma_f32_16x16x32_bf16 v[102:105], v[204:207], v[180:183], v[102:105]
	v_mfma_f32_16x16x32_bf16 v[94:97], v[212:215], v[180:183], v[94:97]
	v_mfma_f32_16x16x32_bf16 v[86:89], v[204:207], v[188:191], v[86:89]
	v_mfma_f32_16x16x32_bf16 v[78:81], v[212:215], v[188:191], v[78:81]
	v_mfma_f32_16x16x32_bf16 v[70:73], v[204:207], v[196:199], v[70:73]
	v_mfma_f32_16x16x32_bf16 v[66:69], v[212:215], v[196:199], v[66:69]
	v_mfma_f32_16x16x32_bf16 v[118:121], v[208:211], v[176:179], v[118:121]
	v_mfma_f32_16x16x32_bf16 v[110:113], v[216:219], v[176:179], v[110:113]
	v_mfma_f32_16x16x32_bf16 v[102:105], v[208:211], v[184:187], v[102:105]
	v_mfma_f32_16x16x32_bf16 v[94:97], v[216:219], v[184:187], v[94:97]
	v_mfma_f32_16x16x32_bf16 v[86:89], v[208:211], v[192:195], v[86:89]
	v_mfma_f32_16x16x32_bf16 v[78:81], v[216:219], v[192:195], v[78:81]
	v_mfma_f32_16x16x32_bf16 v[70:73], v[208:211], v[200:203], v[70:73]
	v_mfma_f32_16x16x32_bf16 v[66:69], v[216:219], v[200:203], v[66:69]
	s_setprio 0
	s_mov_b32 m0, s57
	v_lshl_add_u64 v[158:159], v[220:221], 0, s[14:15]
	s_barrier
	ds_read_b128 v[172:175], v170 offset:49152
	ds_read_b128 v[176:179], v170 offset:50176
	ds_read_b128 v[180:183], v170 offset:51200
	ds_read_b128 v[184:187], v170 offset:52224
	ds_read_b128 v[188:191], v170 offset:53248
	ds_read_b128 v[192:195], v170 offset:54272
	ds_read_b128 v[196:199], v170 offset:55296
	ds_read_b128 v[200:203], v170 offset:56320
	global_load_lds_dwordx4 v[158:159], off
	v_lshl_add_u64 v[158:159], v[222:223], 0, s[14:15]
	s_mov_b32 m0, s58
	s_nop 0
	global_load_lds_dwordx4 v[158:159], off
	s_barrier
	s_waitcnt lgkmcnt(0)
	s_setprio 1
	s_waitcnt lgkmcnt(0)
	v_mfma_f32_16x16x32_bf16 v[62:65], v[130:133], v[172:175], v[62:65]
	v_mfma_f32_16x16x32_bf16 v[58:61], v[138:141], v[172:175], v[58:61]
	v_mfma_f32_16x16x32_bf16 v[54:57], v[130:133], v[180:183], v[54:57]
	v_mfma_f32_16x16x32_bf16 v[46:49], v[138:141], v[180:183], v[46:49]
	v_mfma_f32_16x16x32_bf16 v[38:41], v[130:133], v[188:191], v[38:41]
	v_mfma_f32_16x16x32_bf16 v[30:33], v[138:141], v[188:191], v[30:33]
	v_mfma_f32_16x16x32_bf16 v[22:25], v[130:133], v[196:199], v[22:25]
	v_mfma_f32_16x16x32_bf16 v[14:17], v[138:141], v[196:199], v[14:17]
	v_mfma_f32_16x16x32_bf16 v[62:65], v[134:137], v[176:179], v[62:65]
	v_mfma_f32_16x16x32_bf16 v[58:61], v[142:145], v[176:179], v[58:61]
	v_mfma_f32_16x16x32_bf16 v[54:57], v[134:137], v[184:187], v[54:57]
	v_mfma_f32_16x16x32_bf16 v[46:49], v[142:145], v[184:187], v[46:49]
	v_mfma_f32_16x16x32_bf16 v[38:41], v[134:137], v[192:195], v[38:41]
	v_mfma_f32_16x16x32_bf16 v[30:33], v[142:145], v[192:195], v[30:33]
	v_mfma_f32_16x16x32_bf16 v[22:25], v[134:137], v[200:203], v[22:25]
	v_mfma_f32_16x16x32_bf16 v[14:17], v[142:145], v[200:203], v[14:17]
	s_setprio 0
	s_barrier
	s_add_u32 s40, s40, 0x80080
	s_addc_u32 s41, s41, 0
	s_add_i32 s42, s42, s47
	v_lshl_add_u64 v[130:131], s[40:41], 0, v[146:147]
	s_mov_b32 m0, s42
	s_nop 0
	global_load_lds_dwordx4 v[130:131], off
	v_lshl_add_u64 v[130:131], s[40:41], 0, v[148:149]
	s_add_i32 m0, s42, 0x2000
	s_nop 0
	global_load_lds_dwordx4 v[130:131], off
	s_waitcnt vmcnt(6)
	s_barrier
	s_setprio 1
	v_mfma_f32_16x16x32_bf16 v[50:53], v[204:207], v[172:175], v[50:53]
	v_mfma_f32_16x16x32_bf16 v[42:45], v[212:215], v[172:175], v[42:45]
	v_mfma_f32_16x16x32_bf16 v[34:37], v[204:207], v[180:183], v[34:37]
	v_mfma_f32_16x16x32_bf16 v[26:29], v[212:215], v[180:183], v[26:29]
	v_mfma_f32_16x16x32_bf16 v[18:21], v[204:207], v[188:191], v[18:21]
	v_mfma_f32_16x16x32_bf16 v[10:13], v[212:215], v[188:191], v[10:13]
	v_mfma_f32_16x16x32_bf16 v[6:9], v[204:207], v[196:199], v[6:9]
	v_mfma_f32_16x16x32_bf16 v[2:5], v[212:215], v[196:199], v[2:5]
	v_mfma_f32_16x16x32_bf16 v[50:53], v[208:211], v[176:179], v[50:53]
	v_mfma_f32_16x16x32_bf16 v[42:45], v[216:219], v[176:179], v[42:45]
	v_mfma_f32_16x16x32_bf16 v[34:37], v[208:211], v[184:187], v[34:37]
	v_mfma_f32_16x16x32_bf16 v[26:29], v[216:219], v[184:187], v[26:29]
	v_mfma_f32_16x16x32_bf16 v[18:21], v[208:211], v[192:195], v[18:21]
	v_mfma_f32_16x16x32_bf16 v[10:13], v[216:219], v[192:195], v[10:13]
	v_mfma_f32_16x16x32_bf16 v[6:9], v[208:211], v[200:203], v[6:9]
	v_mfma_f32_16x16x32_bf16 v[2:5], v[216:219], v[200:203], v[2:5]
	s_setprio 0
	s_add_i32 s67, s67, 2
	s_add_u32 s38, s38, 0x100
	s_addc_u32 s39, s39, 0
	s_add_u32 s65, s65, 0x100
	s_addc_u32 s66, s66, 0
	s_cmp_gt_u32 s67, 29
	s_barrier
	s_cbranch_scc0 .LBB0_945
	s_branch .Lp6_loop_exit

.LBB0_1292:
	v_cndmask_b32_e64 v2, 0, 1, s[6:7]
	v_cmp_ne_u32_e64 s[8:9], 1, v2
	s_andn2_b64 vcc, exec, s[6:7]
	s_add_u32 s6, s28, 0x2b00
	s_addc_u32 s7, s29, 0
	s_cbranch_vccnz .LBB0_1294
	s_mul_i32 s6, s55, 0x2c0000
	s_mul_hi_i32 s7, s55, 0x2c0000
	s_add_u32 s6, s41, s6
	s_addc_u32 s7, s42, s7
.LBB0_1294:
	s_and_b64 vcc, exec, s[8:9]
	s_add_u32 s8, s30, 0x2b00
	s_addc_u32 s9, s31, 0
	s_cbranch_vccnz .LBB0_1296
	s_mul_i32 s8, s54, 0x2c0000
	s_mul_hi_i32 s9, s54, 0x2c0000
	s_add_u32 s8, s3, s8
	s_addc_u32 s9, s36, s9
